# sample-row mini GEMMs (3 phases): second k-half operand loads get their own registers and are issued together with the first half (one load latency per tile instead of two)
# baseline (speedup 1.0000x reference)
.LBB0_654:
	s_ashr_i32 s4, s12, 31
	s_lshr_b32 s4, s4, 28
	s_add_i32 s4, s12, s4
	s_ashr_i32 s4, s4, 4
	s_add_i32 s5, s4, s13
	s_lshl_b32 s4, s4, 10
	s_sub_i32 s4, s8, s4
	v_add_u32_e32 v28, s4, v1
	v_ashrrev_i32_e32 v29, 31, v28
	v_lshlrev_b64 v[28:29], 11, v[28:29]
	s_lshl_b32 s16, s5, 6
	v_lshl_add_u64 v[128:129], v[10:11], 0, v[28:29]
	s_add_i32 s16, s16, 0x8000
	v_add_co_u32_e32 v144, vcc, s15, v128
	v_or_b32_e32 v30, s16, v1
	s_nop 0
	v_addc_co_u32_e32 v145, vcc, 0, v129, vcc
	v_ashrrev_i32_e32 v31, 31, v30
	v_add_co_u32_e32 v146, vcc, s10, v128
	v_lshlrev_b64 v[30:31], 11, v[30:31]
	s_nop 0
	v_addc_co_u32_e32 v147, vcc, 0, v129, vcc
	v_lshl_add_u64 v[130:131], v[4:5], 0, v[30:31]
	v_add_co_u32_e32 v148, vcc, s11, v128
	v_lshl_add_u64 v[56:57], v[130:131], 0, v[6:7]
	s_nop 0
	v_addc_co_u32_e32 v149, vcc, 0, v129, vcc
	v_add_co_u32_e32 v68, vcc, s15, v56
	global_load_dwordx4 v[28:31], v[128:129], off
	global_load_dwordx4 v[32:35], v[128:129], off offset:64
	v_addc_co_u32_e32 v69, vcc, 0, v57, vcc
	v_add_co_u32_e32 v80, vcc, s10, v56
	global_load_dwordx4 v[36:39], v[144:145], off
	global_load_dwordx4 v[40:43], v[146:147], off
	global_load_dwordx4 v[44:47], v[148:149], off
	global_load_dwordx4 v[48:51], v[56:57], off
	global_load_dwordx4 v[52:55], v[56:57], off offset:64
	v_addc_co_u32_e32 v81, vcc, 0, v57, vcc
	v_add_co_u32_e32 v92, vcc, s11, v56
	global_load_dwordx4 v[60:63], v[68:69], off
	global_load_dwordx4 v[64:67], v[68:69], off offset:64
	v_addc_co_u32_e32 v93, vcc, 0, v57, vcc
	global_load_dwordx4 v[72:75], v[80:81], off
	global_load_dwordx4 v[76:79], v[80:81], off offset:64
	global_load_dwordx4 v[84:87], v[92:93], off
	global_load_dwordx4 v[88:91], v[92:93], off offset:64
	global_load_dwordx4 v[100:103], v[146:147], off offset:64
	global_load_dwordx4 v[108:111], v[148:149], off offset:64
	v_lshl_add_u64 v[136:137], v[130:131], 0, v[8:9]
	global_load_dwordx4 v[92:95], v[144:145], off offset:64
	global_load_dwordx4 v[152:155], v[128:129], off offset:128
	global_load_dwordx4 v[156:159], v[128:129], off offset:192
	v_add_co_u32_e32 v220, vcc, s15, v136
	s_nop 1
	v_addc_co_u32_e32 v221, vcc, 0, v137, vcc
	v_add_co_u32_e32 v222, vcc, s10, v136
	s_nop 1
	v_addc_co_u32_e32 v223, vcc, 0, v137, vcc
	v_add_co_u32_e32 v224, vcc, s11, v136
	s_nop 1
	global_load_dwordx4 v[160:163], v[144:145], off offset:128
	global_load_dwordx4 v[164:167], v[146:147], off offset:128
	global_load_dwordx4 v[168:171], v[148:149], off offset:128
	v_addc_co_u32_e32 v225, vcc, 0, v137, vcc
	global_load_dwordx4 v[172:175], v[136:137], off
	global_load_dwordx4 v[176:179], v[136:137], off offset:64
	global_load_dwordx4 v[180:183], v[220:221], off
	global_load_dwordx4 v[188:191], v[220:221], off offset:64
	global_load_dwordx4 v[192:195], v[222:223], off
	global_load_dwordx4 v[196:199], v[222:223], off offset:64
	global_load_dwordx4 v[200:203], v[224:225], off
	global_load_dwordx4 v[204:207], v[224:225], off offset:64
	global_load_dwordx4 v[208:211], v[148:149], off offset:192
	global_load_dwordx4 v[212:215], v[144:145], off offset:192
	global_load_dwordx4 v[216:219], v[146:147], off offset:192
	s_ashr_i32 s5, s4, 31
	s_add_i32 s12, s12, s14
	s_add_i32 s8, s8, s9
	s_cmp_lt_i32 s12, 32
	s_waitcnt vmcnt(26)
	v_mfma_f32_16x16x32_bf16 v[56:59], v[28:31], v[48:51], 0
	s_waitcnt vmcnt(24)
	v_mfma_f32_16x16x32_bf16 v[68:71], v[28:31], v[60:63], 0
	s_waitcnt vmcnt(22)
	v_mfma_f32_16x16x32_bf16 v[80:83], v[28:31], v[72:75], 0
	s_waitcnt vmcnt(20)
	v_mfma_f32_16x16x32_bf16 v[28:31], v[28:31], v[84:87], 0
	v_mfma_f32_16x16x32_bf16 v[96:99], v[36:39], v[48:51], 0
	v_mfma_f32_16x16x32_bf16 v[104:107], v[40:43], v[48:51], 0
	v_mfma_f32_16x16x32_bf16 v[48:51], v[44:47], v[48:51], 0
	v_mfma_f32_16x16x32_bf16 v[112:115], v[36:39], v[60:63], 0
	v_mfma_f32_16x16x32_bf16 v[116:119], v[40:43], v[60:63], 0
	v_mfma_f32_16x16x32_bf16 v[60:63], v[44:47], v[60:63], 0
	v_mfma_f32_16x16x32_bf16 v[120:123], v[36:39], v[72:75], 0
	v_mfma_f32_16x16x32_bf16 v[36:39], v[36:39], v[84:87], 0
	v_mfma_f32_16x16x32_bf16 v[124:127], v[40:43], v[72:75], 0
	v_mfma_f32_16x16x32_bf16 v[72:75], v[44:47], v[72:75], 0
	v_mfma_f32_16x16x32_bf16 v[40:43], v[40:43], v[84:87], 0
	v_mfma_f32_16x16x32_bf16 v[44:47], v[44:47], v[84:87], 0
	v_mfma_f32_16x16x32_bf16 v[56:59], v[32:35], v[52:55], v[56:59]
	v_mfma_f32_16x16x32_bf16 v[68:71], v[32:35], v[64:67], v[68:71]
	v_mfma_f32_16x16x32_bf16 v[80:83], v[32:35], v[76:79], v[80:83]
	s_waitcnt vmcnt(19)
	v_mfma_f32_16x16x32_bf16 v[28:31], v[32:35], v[88:91], v[28:31]
	s_waitcnt vmcnt(16)
	v_mfma_f32_16x16x32_bf16 v[32:35], v[92:95], v[52:55], v[96:99]
	v_mfma_f32_16x16x32_bf16 v[84:87], v[100:103], v[52:55], v[104:107]
	v_mfma_f32_16x16x32_bf16 v[48:51], v[108:111], v[52:55], v[48:51]
	v_mfma_f32_16x16x32_bf16 v[52:55], v[92:95], v[64:67], v[112:115]
	s_nop 0
	s_nop 0
	v_mfma_f32_16x16x32_bf16 v[96:99], v[100:103], v[64:67], v[116:119]
	v_mfma_f32_16x16x32_bf16 v[60:63], v[108:111], v[64:67], v[60:63]
	v_mfma_f32_16x16x32_bf16 v[64:67], v[92:95], v[76:79], v[120:123]
	v_mfma_f32_16x16x32_bf16 v[36:39], v[92:95], v[88:91], v[36:39]
	v_add_co_u32_e32 v92, vcc, s15, v136
	s_nop 1
	v_addc_co_u32_e32 v93, vcc, 0, v137, vcc
	v_add_co_u32_e32 v138, vcc, s10, v136
	v_mfma_f32_16x16x32_bf16 v[116:119], v[100:103], v[76:79], v[124:127]
	s_nop 0
	v_addc_co_u32_e32 v139, vcc, 0, v137, vcc
	v_add_co_u32_e32 v140, vcc, s11, v136
	v_addc_co_u32_e32 v141, vcc, 0, v137, vcc
	v_mfma_f32_16x16x32_bf16 v[72:75], v[108:111], v[76:79], v[72:75]
	v_mfma_f32_16x16x32_bf16 v[40:43], v[100:103], v[88:91], v[40:43]
	v_mfma_f32_16x16x32_bf16 v[44:47], v[108:111], v[88:91], v[44:47]
	s_nop 0
	s_nop 0
	s_nop 0
	s_nop 0
	s_waitcnt vmcnt(0)
	v_mfma_f32_16x16x32_bf16 v[56:59], v[152:155], v[172:175], v[56:59]
	v_mfma_f32_16x16x32_bf16 v[68:71], v[152:155], v[180:183], v[68:71]
	v_mfma_f32_16x16x32_bf16 v[80:83], v[152:155], v[192:195], v[80:83]
	v_mfma_f32_16x16x32_bf16 v[28:31], v[152:155], v[200:203], v[28:31]
	s_nop 0
	v_mfma_f32_16x16x32_bf16 v[32:35], v[160:163], v[172:175], v[32:35]
	s_barrier
	v_mfma_f32_16x16x32_bf16 v[84:87], v[164:167], v[172:175], v[84:87]
	v_mfma_f32_16x16x32_bf16 v[48:51], v[168:171], v[172:175], v[48:51]
	v_mfma_f32_16x16x32_bf16 v[52:55], v[160:163], v[180:183], v[52:55]
	v_mfma_f32_16x16x32_bf16 v[76:79], v[164:167], v[180:183], v[96:99]
	v_mfma_f32_16x16x32_bf16 v[60:63], v[168:171], v[180:183], v[60:63]
	v_mfma_f32_16x16x32_bf16 v[64:67], v[160:163], v[192:195], v[64:67]
	v_mfma_f32_16x16x32_bf16 v[88:91], v[164:167], v[192:195], v[116:119]
	v_mfma_f32_16x16x32_bf16 v[72:75], v[168:171], v[192:195], v[72:75]
	v_mfma_f32_16x16x32_bf16 v[36:39], v[160:163], v[200:203], v[36:39]
	v_mfma_f32_16x16x32_bf16 v[40:43], v[164:167], v[200:203], v[40:43]
	v_mfma_f32_16x16x32_bf16 v[44:47], v[168:171], v[200:203], v[44:47]
	v_mfma_f32_16x16x32_bf16 v[56:59], v[156:159], v[176:179], v[56:59]
	v_mfma_f32_16x16x32_bf16 v[32:35], v[212:215], v[176:179], v[32:35]
	v_mfma_f32_16x16x32_bf16 v[84:87], v[216:219], v[176:179], v[84:87]
	v_mfma_f32_16x16x32_bf16 v[48:51], v[208:211], v[176:179], v[48:51]
	v_mfma_f32_16x16x32_bf16 v[68:71], v[156:159], v[188:191], v[68:71]
	v_mfma_f32_16x16x32_bf16 v[80:83], v[156:159], v[196:199], v[80:83]
	v_mfma_f32_16x16x32_bf16 v[28:31], v[156:159], v[204:207], v[28:31]
	v_mfma_f32_16x16x32_bf16 v[52:55], v[212:215], v[188:191], v[52:55]
	v_mfma_f32_16x16x32_bf16 v[76:79], v[216:219], v[188:191], v[76:79]
	v_mfma_f32_16x16x32_bf16 v[60:63], v[208:211], v[188:191], v[60:63]
	v_add_u32_e32 v92, s16, v12
	v_ashrrev_i32_e32 v93, 31, v92
	v_lshlrev_b64 v[92:93], 11, v[92:93]
	v_mfma_f32_16x16x32_bf16 v[64:67], v[212:215], v[196:199], v[64:67]
	v_lshl_add_u64 v[92:93], s[6:7], 0, v[92:93]
	v_lshl_add_u64 v[92:93], s[4:5], 1, v[92:93]
	v_lshl_add_u64 v[92:93], v[92:93], 0, v[2:3]
	v_mfma_f32_16x16x32_bf16 v[88:91], v[216:219], v[196:199], v[88:91]
	v_mfma_f32_16x16x32_bf16 v[72:75], v[208:211], v[196:199], v[72:75]
	v_mfma_f32_16x16x32_bf16 v[36:39], v[212:215], v[204:207], v[36:39]
	v_mfma_f32_16x16x32_bf16 v[40:43], v[216:219], v[204:207], v[40:43]
	v_mfma_f32_16x16x32_bf16 v[44:47], v[208:211], v[204:207], v[44:47]
	ds_write_b128 v13, v[56:59]
	ds_write_b128 v14, v[32:35]
	ds_write_b128 v15, v[84:87]
	ds_write_b128 v16, v[48:51]
	ds_write_b128 v13, v[68:71] offset:4096
	ds_write_b128 v14, v[52:55] offset:4096
	ds_write_b128 v15, v[76:79] offset:4096
	ds_write_b128 v16, v[60:63] offset:4096
	ds_write_b128 v13, v[80:83] offset:8192
	ds_write_b128 v14, v[64:67] offset:8192
	ds_write_b128 v15, v[88:91] offset:8192
	ds_write_b128 v16, v[72:75] offset:8192
	ds_write_b128 v13, v[28:31] offset:12288
	ds_write_b128 v14, v[36:39] offset:12288
	ds_write_b128 v15, v[40:43] offset:12288
	ds_write_b128 v16, v[44:47] offset:12288
	s_waitcnt lgkmcnt(0)
	s_waitcnt lgkmcnt(0)
	s_barrier
	ds_read_b128 v[28:31], v17
	ds_read_b128 v[32:35], v17 offset:16384
	ds_read_b128 v[36:39], v18
	ds_read_b128 v[40:43], v18 offset:16384
	ds_read_b128 v[44:47], v17 offset:32768
	ds_read_b128 v[48:51], v17 offset:49152
	ds_read_b128 v[52:55], v18 offset:32768
	ds_read_b128 v[56:59], v18 offset:49152
	ds_read_b128 v[60:63], v19
	ds_read_b128 v[64:67], v20
	ds_read_b128 v[68:71], v21
	ds_read_b128 v[72:75], v22
	ds_read_b128 v[76:79], v23
	ds_read_b128 v[80:83], v24
	ds_read_b128 v[84:87], v25
	ds_read_b128 v[88:91], v26
	s_waitcnt lgkmcnt(14)
	v_pk_add_f32 v[30:31], v[30:31], 0 op_sel_hi:[1,0]
	v_pk_add_f32 v[28:29], v[28:29], 0 op_sel_hi:[1,0]
	s_waitcnt lgkmcnt(13)
	v_pk_add_f32 v[38:39], v[38:39], 0 op_sel_hi:[1,0]
	v_pk_add_f32 v[36:37], v[36:37], 0 op_sel_hi:[1,0]
	v_pk_add_f32 v[30:31], v[30:31], v[34:35]
	v_pk_add_f32 v[28:29], v[28:29], v[32:33]
	s_waitcnt lgkmcnt(12)
	v_pk_add_f32 v[32:33], v[38:39], v[42:43]
	v_pk_add_f32 v[34:35], v[36:37], v[40:41]
	s_waitcnt lgkmcnt(11)
	v_pk_add_f32 v[30:31], v[30:31], v[46:47]
	v_pk_add_f32 v[28:29], v[28:29], v[44:45]
	s_waitcnt lgkmcnt(9)
	v_pk_add_f32 v[32:33], v[32:33], v[54:55]
	v_pk_add_f32 v[34:35], v[34:35], v[52:53]
	v_pk_add_f32 v[30:31], v[30:31], v[50:51]
	v_pk_add_f32 v[28:29], v[28:29], v[48:49]
	s_waitcnt lgkmcnt(8)
	v_pk_add_f32 v[32:33], v[32:33], v[58:59]
	v_pk_add_f32 v[34:35], v[34:35], v[56:57]
	s_waitcnt lgkmcnt(7)
	v_pk_add_f32 v[30:31], v[30:31], v[62:63]
	v_pk_add_f32 v[28:29], v[28:29], v[60:61]
	s_waitcnt lgkmcnt(6)
	v_pk_add_f32 v[32:33], v[32:33], v[66:67]
	v_pk_add_f32 v[34:35], v[34:35], v[64:65]
	s_waitcnt lgkmcnt(5)
	v_pk_add_f32 v[30:31], v[30:31], v[70:71]
	v_pk_add_f32 v[28:29], v[28:29], v[68:69]
	s_waitcnt lgkmcnt(4)
	v_pk_add_f32 v[32:33], v[32:33], v[74:75]
	v_pk_add_f32 v[34:35], v[34:35], v[72:73]
	s_waitcnt lgkmcnt(3)
	v_pk_add_f32 v[30:31], v[30:31], v[78:79]
	v_pk_add_f32 v[28:29], v[28:29], v[76:77]
	s_waitcnt lgkmcnt(2)
	v_pk_add_f32 v[32:33], v[32:33], v[82:83]
	v_pk_add_f32 v[34:35], v[34:35], v[80:81]
	s_waitcnt lgkmcnt(1)
	v_pk_add_f32 v[30:31], v[30:31], v[86:87]
	v_pk_add_f32 v[28:29], v[28:29], v[84:85]
	s_waitcnt lgkmcnt(0)
	v_pk_add_f32 v[32:33], v[32:33], v[90:91]
	v_pk_add_f32 v[34:35], v[34:35], v[88:89]
	v_cvt_pk_bf16_f32 v28, v28, v29
	v_cvt_pk_bf16_f32 v29, v30, v31
	s_nop 0
	v_cvt_pk_bf16_f32 v30, v34, v35
	v_cvt_pk_bf16_f32 v31, v32, v33
	s_nop 0
	global_store_dwordx4 v[92:93], v[28:31], off sc0 sc1
	s_nop 1
	s_cbranch_scc1 .LBB0_654

.LBB0_853:
	s_ashr_i32 s4, s14, 31
	s_lshr_b32 s4, s4, 27
	s_add_i32 s6, s14, s4
	s_ashr_i32 s7, s6, 5
	s_add_i32 s4, s7, s15
	s_lshl_b32 s4, s4, 6
	s_add_i32 s4, s4, 0x8000
	v_or_b32_e32 v16, s4, v1
	v_ashrrev_i32_e32 v17, 31, v16
	v_lshlrev_b64 v[16:17], 11, v[16:17]
	v_lshl_add_u64 v[130:131], v[4:5], 0, v[16:17]
	s_lshl_b32 s7, s7, 11
	v_lshl_add_u64 v[56:57], v[130:131], 0, v[6:7]
	v_subrev_u32_e32 v12, s7, v21
	v_add_co_u32_e32 v72, vcc, s11, v56
	v_ashrrev_i32_e32 v13, 31, v12
	s_nop 0
	v_addc_co_u32_e32 v73, vcc, 0, v57, vcc
	v_lshlrev_b64 v[12:13], 11, v[12:13]
	v_add_co_u32_e32 v76, vcc, s12, v56
	v_lshl_add_u64 v[128:129], v[10:11], 0, v[12:13]
	s_nop 0
	v_addc_co_u32_e32 v77, vcc, 0, v57, vcc
	v_add_co_u32_e32 v132, vcc, s11, v128
	global_load_dwordx4 v[12:15], v[128:129], off
	s_nop 0
	v_addc_co_u32_e32 v133, vcc, 0, v129, vcc
	v_add_co_u32_e32 v92, vcc, s13, v56
	global_load_dwordx4 v[16:19], v[56:57], off
	global_load_dwordx4 v[36:39], v[72:73], off
	v_addc_co_u32_e32 v93, vcc, 0, v57, vcc
	global_load_dwordx4 v[40:43], v[76:77], off
	global_load_dwordx4 v[44:47], v[128:129], off offset:64
	global_load_dwordx4 v[48:51], v[132:133], off
	v_add_co_u32_e32 v134, vcc, s12, v128
	global_load_dwordx4 v[52:55], v[92:93], off
	s_nop 0
	v_addc_co_u32_e32 v135, vcc, 0, v129, vcc
	v_add_co_u32_e32 v136, vcc, s13, v128
	global_load_dwordx4 v[56:59], v[56:57], off offset:64
	s_nop 0
	v_addc_co_u32_e32 v137, vcc, 0, v129, vcc
	global_load_dwordx4 v[64:67], v[134:135], off
	global_load_dwordx4 v[68:71], v[72:73], off offset:64
	v_lshl_add_u64 v[140:141], v[130:131], 0, v[8:9]
	global_load_dwordx4 v[76:79], v[76:77], off offset:64
	s_nop 0
	global_load_dwordx4 v[84:87], v[136:137], off
	global_load_dwordx4 v[88:91], v[92:93], off offset:64
	global_load_dwordx4 v[100:103], v[134:135], off offset:64
	global_load_dwordx4 v[108:111], v[136:137], off offset:64
	s_andn2_b32 s6, s6, 31
	global_load_dwordx4 v[92:95], v[132:133], off offset:64
	global_load_dwordx4 v[152:155], v[128:129], off offset:128
	global_load_dwordx4 v[156:159], v[140:141], off
	global_load_dwordx4 v[160:163], v[132:133], off offset:128
	global_load_dwordx4 v[164:167], v[140:141], off offset:64
	global_load_dwordx4 v[168:171], v[128:129], off offset:192
	global_load_dwordx4 v[172:175], v[134:135], off offset:128
	global_load_dwordx4 v[176:179], v[132:133], off offset:192
	global_load_dwordx4 v[180:183], v[136:137], off offset:128
	global_load_dwordx4 v[188:191], v[134:135], off offset:192
	v_add_co_u32_e32 v220, vcc, s11, v140
	s_nop 1
	v_addc_co_u32_e32 v221, vcc, 0, v141, vcc
	global_load_dwordx4 v[192:195], v[136:137], off offset:192
	v_add_co_u32_e32 v222, vcc, s12, v140
	s_nop 1
	v_addc_co_u32_e32 v223, vcc, 0, v141, vcc
	v_add_co_u32_e32 v224, vcc, s13, v140
	s_nop 1
	global_load_dwordx4 v[196:199], v[220:221], off
	global_load_dwordx4 v[200:203], v[220:221], off offset:64
	v_addc_co_u32_e32 v225, vcc, 0, v141, vcc
	global_load_dwordx4 v[204:207], v[222:223], off
	global_load_dwordx4 v[208:211], v[222:223], off offset:64
	global_load_dwordx4 v[212:215], v[224:225], off
	global_load_dwordx4 v[216:219], v[224:225], off offset:64
	s_sub_i32 s17, s14, s6
	s_cmp_lt_i32 s17, 16
	s_mov_b64 s[6:7], 0x9700000
	s_waitcnt vmcnt(30)
	v_mfma_f32_16x16x32_bf16 v[60:63], v[12:15], v[16:19], 0
	s_waitcnt vmcnt(29)
	v_mfma_f32_16x16x32_bf16 v[72:75], v[12:15], v[36:39], 0
	s_waitcnt vmcnt(28)
	v_mfma_f32_16x16x32_bf16 v[80:83], v[12:15], v[40:43], 0
	s_waitcnt vmcnt(25)
	v_mfma_f32_16x16x32_bf16 v[12:15], v[12:15], v[52:55], 0
	v_mfma_f32_16x16x32_bf16 v[96:99], v[48:51], v[16:19], 0
	s_waitcnt vmcnt(23)
	v_mfma_f32_16x16x32_bf16 v[104:107], v[64:67], v[16:19], 0
	s_waitcnt vmcnt(20)
	v_mfma_f32_16x16x32_bf16 v[16:19], v[84:87], v[16:19], 0
	v_mfma_f32_16x16x32_bf16 v[112:115], v[48:51], v[36:39], 0
	v_mfma_f32_16x16x32_bf16 v[116:119], v[64:67], v[36:39], 0
	v_mfma_f32_16x16x32_bf16 v[36:39], v[84:87], v[36:39], 0
	v_mfma_f32_16x16x32_bf16 v[120:123], v[48:51], v[40:43], 0
	v_mfma_f32_16x16x32_bf16 v[124:127], v[64:67], v[40:43], 0
	v_mfma_f32_16x16x32_bf16 v[48:51], v[48:51], v[52:55], 0
	v_mfma_f32_16x16x32_bf16 v[64:67], v[64:67], v[52:55], 0
	v_mfma_f32_16x16x32_bf16 v[40:43], v[84:87], v[40:43], 0
	v_mfma_f32_16x16x32_bf16 v[52:55], v[84:87], v[52:55], 0
	v_mfma_f32_16x16x32_bf16 v[60:63], v[44:47], v[56:59], v[60:63]
	v_mfma_f32_16x16x32_bf16 v[72:75], v[44:47], v[68:71], v[72:75]
	s_waitcnt vmcnt(16)
	v_mfma_f32_16x16x32_bf16 v[84:87], v[92:95], v[56:59], v[96:99]
	v_mfma_f32_16x16x32_bf16 v[96:99], v[100:103], v[56:59], v[104:107]
	v_mfma_f32_16x16x32_bf16 v[16:19], v[108:111], v[56:59], v[16:19]
	v_mfma_f32_16x16x32_bf16 v[56:59], v[92:95], v[68:71], v[112:115]
	v_mfma_f32_16x16x32_bf16 v[104:107], v[100:103], v[68:71], v[116:119]
	v_mfma_f32_16x16x32_bf16 v[36:39], v[108:111], v[68:71], v[36:39]
	v_mfma_f32_16x16x32_bf16 v[68:71], v[44:47], v[76:79], v[80:83]
	v_mfma_f32_16x16x32_bf16 v[12:15], v[44:47], v[88:91], v[12:15]
	v_mfma_f32_16x16x32_bf16 v[44:47], v[92:95], v[88:91], v[48:51]
	v_mfma_f32_16x16x32_bf16 v[48:51], v[100:103], v[88:91], v[64:67]
	s_nop 2
	v_mfma_f32_16x16x32_bf16 v[80:83], v[92:95], v[76:79], v[120:123]
	v_mfma_f32_16x16x32_bf16 v[112:115], v[100:103], v[76:79], v[124:127]
	v_mfma_f32_16x16x32_bf16 v[40:43], v[108:111], v[76:79], v[40:43]
	v_mfma_f32_16x16x32_bf16 v[52:55], v[108:111], v[88:91], v[52:55]
	v_add_co_u32_e32 v132, vcc, s11, v140
	s_waitcnt vmcnt(0)
	v_mfma_f32_16x16x32_bf16 v[60:63], v[152:155], v[156:159], v[60:63]
	v_addc_co_u32_e32 v133, vcc, 0, v141, vcc
	v_mfma_f32_16x16x32_bf16 v[84:87], v[160:163], v[156:159], v[84:87]
	v_add_co_u32_e32 v136, vcc, s12, v140
	v_mfma_f32_16x16x32_bf16 v[96:99], v[172:175], v[156:159], v[96:99]
	v_addc_co_u32_e32 v137, vcc, 0, v141, vcc
	v_add_co_u32_e32 v144, vcc, s13, v140
	v_mfma_f32_16x16x32_bf16 v[16:19], v[180:183], v[156:159], v[16:19]
	s_nop 0
	v_addc_co_u32_e32 v145, vcc, 0, v141, vcc
	v_mfma_f32_16x16x32_bf16 v[72:75], v[152:155], v[196:199], v[72:75]
	v_mfma_f32_16x16x32_bf16 v[56:59], v[160:163], v[196:199], v[56:59]
	v_mfma_f32_16x16x32_bf16 v[104:107], v[172:175], v[196:199], v[104:107]
	v_mfma_f32_16x16x32_bf16 v[36:39], v[180:183], v[196:199], v[36:39]
	s_nop 0
	s_nop 0
	v_mfma_f32_16x16x32_bf16 v[68:71], v[152:155], v[204:207], v[68:71]
	v_mfma_f32_16x16x32_bf16 v[80:83], v[160:163], v[204:207], v[80:83]
	v_mfma_f32_16x16x32_bf16 v[112:115], v[172:175], v[204:207], v[112:115]
	v_mfma_f32_16x16x32_bf16 v[40:43], v[180:183], v[204:207], v[40:43]
	s_barrier
	v_mfma_f32_16x16x32_bf16 v[12:15], v[152:155], v[212:215], v[12:15]
	v_mfma_f32_16x16x32_bf16 v[44:47], v[160:163], v[212:215], v[44:47]
	v_mfma_f32_16x16x32_bf16 v[60:63], v[168:171], v[164:167], v[60:63]
	v_mfma_f32_16x16x32_bf16 v[16:19], v[192:195], v[164:167], v[16:19]
	v_mfma_f32_16x16x32_bf16 v[48:51], v[172:175], v[212:215], v[48:51]
	v_mfma_f32_16x16x32_bf16 v[64:67], v[176:179], v[164:167], v[84:87]
	v_mfma_f32_16x16x32_bf16 v[72:75], v[168:171], v[200:203], v[72:75]
	v_mfma_f32_16x16x32_bf16 v[88:91], v[188:191], v[200:203], v[104:107]
	v_mfma_f32_16x16x32_bf16 v[84:87], v[188:191], v[164:167], v[96:99]
	s_nop 1
	ds_write_b128 v22, v[60:63]
	s_nop 1
	ds_write_b128 v23, v[64:67]
	s_nop 1
	ds_write_b128 v24, v[84:87]
	v_mfma_f32_16x16x32_bf16 v[56:59], v[176:179], v[200:203], v[56:59]
	ds_write_b128 v25, v[16:19]
	ds_write_b128 v22, v[72:75] offset:4096
	s_nop 5
	ds_write_b128 v23, v[56:59] offset:4096
	v_mfma_f32_16x16x32_bf16 v[36:39], v[192:195], v[200:203], v[36:39]
	v_mfma_f32_16x16x32_bf16 v[52:55], v[180:183], v[212:215], v[52:55]
	v_mfma_f32_16x16x32_bf16 v[68:71], v[168:171], v[208:211], v[68:71]
	ds_write_b128 v24, v[88:91] offset:4096
	s_nop 4
	ds_write_b128 v25, v[36:39] offset:4096
	s_nop 0
	ds_write_b128 v22, v[68:71] offset:8192
	v_mfma_f32_16x16x32_bf16 v[80:83], v[176:179], v[208:211], v[80:83]
	s_waitcnt vmcnt(0)
	v_mfma_f32_16x16x32_bf16 v[12:15], v[168:171], v[216:219], v[12:15]
	v_mfma_f32_16x16x32_bf16 v[92:95], v[188:191], v[208:211], v[112:115]
	v_mfma_f32_16x16x32_bf16 v[16:19], v[176:179], v[216:219], v[44:47]
	v_mfma_f32_16x16x32_bf16 v[40:43], v[192:195], v[208:211], v[40:43]
	s_nop 2
	ds_write_b128 v23, v[80:83] offset:8192
	s_nop 1
	ds_write_b128 v24, v[92:95] offset:8192
	s_nop 0
	ds_write_b128 v25, v[40:43] offset:8192
	v_mfma_f32_16x16x32_bf16 v[36:39], v[188:191], v[216:219], v[48:51]
	ds_write_b128 v22, v[12:15] offset:12288
	ds_write_b128 v23, v[16:19] offset:12288
	s_nop 5
	ds_write_b128 v24, v[36:39] offset:12288
	v_mfma_f32_16x16x32_bf16 v[12:15], v[192:195], v[216:219], v[52:55]
	s_nop 7
	ds_write_b128 v25, v[12:15] offset:12288
	s_waitcnt lgkmcnt(0)
	s_waitcnt lgkmcnt(0)
	s_barrier
	ds_read_b128 v[12:15], v26
	ds_read_b128 v[16:19], v27
	ds_read_b128 v[36:39], v26 offset:16384
	s_waitcnt lgkmcnt(2)
	v_pk_add_f32 v[40:41], v[14:15], 0 op_sel_hi:[1,0]
	v_pk_add_f32 v[42:43], v[12:13], 0 op_sel_hi:[1,0]
	ds_read_b128 v[12:15], v27 offset:16384
	s_waitcnt lgkmcnt(2)
	v_pk_add_f32 v[44:45], v[18:19], 0 op_sel_hi:[1,0]
	v_pk_add_f32 v[46:47], v[16:17], 0 op_sel_hi:[1,0]
	ds_read_b128 v[16:19], v26 offset:32768
	s_waitcnt lgkmcnt(2)
	v_pk_add_f32 v[40:41], v[40:41], v[38:39]
	v_pk_add_f32 v[42:43], v[42:43], v[36:37]
	s_waitcnt lgkmcnt(1)
	v_pk_add_f32 v[44:45], v[44:45], v[14:15]
	v_pk_add_f32 v[46:47], v[46:47], v[12:13]
	ds_read_b128 v[12:15], v27 offset:32768
	ds_read_b128 v[36:39], v26 offset:49152
	s_waitcnt lgkmcnt(2)
	v_pk_add_f32 v[40:41], v[40:41], v[18:19]
	v_pk_add_f32 v[42:43], v[42:43], v[16:17]
	ds_read_b128 v[16:19], v27 offset:49152
	s_waitcnt lgkmcnt(2)
	v_pk_add_f32 v[44:45], v[44:45], v[14:15]
	v_pk_add_f32 v[46:47], v[46:47], v[12:13]
	ds_read_b128 v[12:15], v28
	s_waitcnt lgkmcnt(2)
	v_pk_add_f32 v[40:41], v[40:41], v[38:39]
	v_pk_add_f32 v[42:43], v[42:43], v[36:37]
	ds_read_b128 v[36:39], v29
	s_waitcnt lgkmcnt(2)
	v_pk_add_f32 v[18:19], v[44:45], v[18:19]
	v_pk_add_f32 v[44:45], v[46:47], v[16:17]
	s_waitcnt lgkmcnt(1)
	v_pk_add_f32 v[46:47], v[40:41], v[14:15]
	ds_read_b128 v[14:17], v30
	v_pk_add_f32 v[12:13], v[42:43], v[12:13]
	s_waitcnt lgkmcnt(1)
	v_pk_add_f32 v[42:43], v[18:19], v[38:39]
	ds_read_b128 v[38:41], v31
	v_pk_add_f32 v[36:37], v[44:45], v[36:37]
	s_waitcnt lgkmcnt(1)
	v_pk_add_f32 v[44:45], v[46:47], v[16:17]
	ds_read_b128 v[16:19], v32
	v_pk_add_f32 v[46:47], v[12:13], v[14:15]
	ds_read_b128 v[12:15], v33
	s_waitcnt lgkmcnt(2)
	v_pk_add_f32 v[48:49], v[42:43], v[40:41]
	v_pk_add_f32 v[50:51], v[36:37], v[38:39]
	ds_read_b128 v[36:39], v34
	ds_read_b128 v[40:43], v35
	s_waitcnt lgkmcnt(3)
	v_pk_add_f32 v[18:19], v[44:45], v[18:19]
	v_pk_add_f32 v[16:17], v[46:47], v[16:17]
	s_waitcnt lgkmcnt(2)
	v_pk_add_f32 v[44:45], v[48:49], v[14:15]
	v_pk_add_f32 v[46:47], v[50:51], v[12:13]
	s_waitcnt lgkmcnt(1)
	v_pk_add_f32 v[14:15], v[18:19], v[38:39]
	v_pk_add_f32 v[18:19], v[16:17], v[36:37]
	s_waitcnt lgkmcnt(0)
	v_pk_add_f32 v[12:13], v[44:45], v[42:43]
	v_pk_add_f32 v[16:17], v[46:47], v[40:41]
	s_cbranch_scc1 .LBB0_852
	v_mul_f32_e32 v36, 0xbfb8aa3b, v18
	v_mul_f32_e32 v37, 0xbfb8aa3b, v19
	v_mul_f32_e32 v38, 0xbfb8aa3b, v14
	v_mul_f32_e32 v39, 0xbfb8aa3b, v15
	v_mul_f32_e32 v40, 0xbfb8aa3b, v16
	v_mul_f32_e32 v41, 0xbfb8aa3b, v17
	v_mul_f32_e32 v42, 0xbfb8aa3b, v12
	v_mul_f32_e32 v43, 0xbfb8aa3b, v13
	v_exp_f32_e32 v36, v36
	v_exp_f32_e32 v37, v37
	v_exp_f32_e32 v38, v38
	v_exp_f32_e32 v39, v39
	v_exp_f32_e32 v40, v40
	v_exp_f32_e32 v41, v41
	v_exp_f32_e32 v42, v42
	v_exp_f32_e32 v43, v43
	v_add_f32_e32 v36, 1.0, v36
	v_add_f32_e32 v37, 1.0, v37
	v_add_f32_e32 v38, 1.0, v38
	v_add_f32_e32 v39, 1.0, v39
	v_add_f32_e32 v40, 1.0, v40
	v_add_f32_e32 v41, 1.0, v41
	v_add_f32_e32 v42, 1.0, v42
	v_add_f32_e32 v43, 1.0, v43
	v_rcp_f32_e32 v36, v36
	v_rcp_f32_e32 v37, v37
	v_rcp_f32_e32 v38, v38
	v_rcp_f32_e32 v39, v39
	v_rcp_f32_e32 v40, v40
	v_rcp_f32_e32 v42, v42
	v_rcp_f32_e32 v43, v43
	v_rcp_f32_e32 v41, v41
	v_pk_mul_f32 v[14:15], v[14:15], v[38:39]
	v_pk_mul_f32 v[18:19], v[18:19], v[36:37]
	v_pk_mul_f32 v[12:13], v[12:13], v[42:43]
	v_pk_mul_f32 v[16:17], v[16:17], v[40:41]
	s_mov_b64 s[6:7], 0xd900000
	s_branch .LBB0_852

.LBB0_1016:
	s_ashr_i32 s2, s4, 31
	s_lshr_b32 s2, s2, 28
	s_add_i32 s2, s4, s2
	s_ashr_i32 s2, s2, 4
	s_add_i32 s3, s2, s5
	s_lshl_b32 s2, s2, 10
	s_sub_i32 s2, s8, s2
	v_add_u32_e32 v26, s2, v10
	v_ashrrev_i32_e32 v27, 31, v26
	v_lshlrev_b64 v[26:27], 11, v[26:27]
	s_lshl_b32 s15, s3, 6
	v_lshl_add_u64 v[126:127], v[8:9], 0, v[26:27]
	s_add_i32 s15, s15, 0x8000
	v_add_co_u32_e32 v142, vcc, s13, v126
	v_or_b32_e32 v28, s15, v10
	s_nop 0
	v_addc_co_u32_e32 v143, vcc, 0, v127, vcc
	v_ashrrev_i32_e32 v29, 31, v28
	v_add_co_u32_e32 v144, vcc, s10, v126
	v_lshlrev_b64 v[28:29], 7, v[28:29]
	s_nop 0
	v_addc_co_u32_e32 v145, vcc, 0, v127, vcc
	v_lshl_add_u64 v[128:129], v[2:3], 0, v[28:29]
	v_add_co_u32_e32 v146, vcc, s11, v126
	v_lshl_add_u64 v[66:67], v[128:129], 0, v[4:5]
	s_nop 0
	v_addc_co_u32_e32 v147, vcc, 0, v127, vcc
	v_add_co_u32_e32 v90, vcc, s14, v66
	global_load_dwordx4 v[26:29], v[126:127], off
	global_load_dwordx4 v[30:33], v[126:127], off offset:64
	v_addc_co_u32_e32 v91, vcc, 0, v67, vcc
	global_load_dwordx4 v[34:37], v[142:143], off
	global_load_dwordx4 v[38:41], v[144:145], off
	global_load_dwordx4 v[42:45], v[146:147], off
	global_load_dwordx4 v[46:49], v[66:67], off
	global_load_dwordx4 v[50:53], v[66:67], off offset:2048
	global_load_dwordx4 v[54:57], v[66:67], off offset:64
	global_load_dwordx4 v[58:61], v[66:67], off offset:2112
	global_load_dwordx4 v[70:73], v[90:91], off
	global_load_dwordx4 v[74:77], v[90:91], off offset:64
	global_load_dwordx4 v[82:85], v[90:91], off offset:2048
	global_load_dwordx4 v[86:89], v[90:91], off offset:2112
	global_load_dwordx4 v[98:101], v[144:145], off offset:64
	global_load_dwordx4 v[106:109], v[146:147], off offset:64
	s_ashr_i32 s3, s2, 31
	global_load_dwordx4 v[90:93], v[142:143], off offset:64
	global_load_dwordx4 v[152:155], v[126:127], off offset:128
	global_load_dwordx4 v[156:159], v[126:127], off offset:192
	v_lshl_add_u64 v[220:221], v[128:129], 0, v[6:7]
	v_add_co_u32_e32 v222, vcc, s14, v220
	s_nop 1
	global_load_dwordx4 v[160:163], v[142:143], off offset:128
	global_load_dwordx4 v[164:167], v[144:145], off offset:128
	global_load_dwordx4 v[168:171], v[146:147], off offset:128
	v_addc_co_u32_e32 v223, vcc, 0, v221, vcc
	global_load_dwordx4 v[172:175], v[220:221], off
	global_load_dwordx4 v[176:179], v[220:221], off offset:2048
	global_load_dwordx4 v[180:183], v[220:221], off offset:64
	global_load_dwordx4 v[188:191], v[220:221], off offset:2112
	global_load_dwordx4 v[192:195], v[222:223], off
	global_load_dwordx4 v[196:199], v[222:223], off offset:64
	global_load_dwordx4 v[200:203], v[222:223], off offset:2048
	global_load_dwordx4 v[204:207], v[222:223], off offset:2112
	global_load_dwordx4 v[208:211], v[146:147], off offset:192
	global_load_dwordx4 v[212:215], v[142:143], off offset:192
	global_load_dwordx4 v[216:219], v[144:145], off offset:192
	s_add_i32 s4, s4, s12
	s_add_i32 s8, s8, s9
	s_cmp_lt_i32 s4, 32
	s_waitcnt vmcnt(26)
	v_mfma_f32_16x16x32_bf16 v[62:65], v[26:29], v[46:49], 0
	s_waitcnt vmcnt(25)
	v_mfma_f32_16x16x32_bf16 v[66:69], v[26:29], v[50:53], 0
	s_waitcnt vmcnt(22)
	v_mfma_f32_16x16x32_bf16 v[78:81], v[26:29], v[70:73], 0
	s_waitcnt vmcnt(20)
	v_mfma_f32_16x16x32_bf16 v[26:29], v[26:29], v[82:85], 0
	v_mfma_f32_16x16x32_bf16 v[94:97], v[34:37], v[46:49], 0
	v_mfma_f32_16x16x32_bf16 v[102:105], v[38:41], v[46:49], 0
	v_mfma_f32_16x16x32_bf16 v[46:49], v[42:45], v[46:49], 0
	v_mfma_f32_16x16x32_bf16 v[110:113], v[34:37], v[50:53], 0
	v_mfma_f32_16x16x32_bf16 v[114:117], v[38:41], v[50:53], 0
	v_mfma_f32_16x16x32_bf16 v[50:53], v[42:45], v[50:53], 0
	v_mfma_f32_16x16x32_bf16 v[118:121], v[34:37], v[70:73], 0
	v_mfma_f32_16x16x32_bf16 v[122:125], v[38:41], v[70:73], 0
	v_mfma_f32_16x16x32_bf16 v[70:73], v[42:45], v[70:73], 0
	v_mfma_f32_16x16x32_bf16 v[34:37], v[34:37], v[82:85], 0
	v_mfma_f32_16x16x32_bf16 v[38:41], v[38:41], v[82:85], 0
	v_mfma_f32_16x16x32_bf16 v[42:45], v[42:45], v[82:85], 0
	v_mfma_f32_16x16x32_bf16 v[62:65], v[30:33], v[54:57], v[62:65]
	v_mfma_f32_16x16x32_bf16 v[66:69], v[30:33], v[58:61], v[66:69]
	v_mfma_f32_16x16x32_bf16 v[78:81], v[30:33], v[74:77], v[78:81]
	s_waitcnt vmcnt(19)
	v_mfma_f32_16x16x32_bf16 v[26:29], v[30:33], v[86:89], v[26:29]
	s_waitcnt vmcnt(16)
	v_mfma_f32_16x16x32_bf16 v[30:33], v[90:93], v[54:57], v[94:97]
	v_mfma_f32_16x16x32_bf16 v[82:85], v[98:101], v[54:57], v[102:105]
	v_mfma_f32_16x16x32_bf16 v[46:49], v[106:109], v[54:57], v[46:49]
	v_mfma_f32_16x16x32_bf16 v[54:57], v[90:93], v[58:61], v[110:113]
	v_mfma_f32_16x16x32_bf16 v[94:97], v[98:101], v[58:61], v[114:117]
	v_mfma_f32_16x16x32_bf16 v[50:53], v[106:109], v[58:61], v[50:53]
	v_mfma_f32_16x16x32_bf16 v[58:61], v[90:93], v[74:77], v[118:121]
	v_mfma_f32_16x16x32_bf16 v[102:105], v[98:101], v[74:77], v[122:125]
	v_mfma_f32_16x16x32_bf16 v[70:73], v[106:109], v[74:77], v[70:73]
	v_lshl_add_u64 v[126:127], v[128:129], 0, v[6:7]
	v_add_co_u32_e32 v138, vcc, s14, v126
	v_mfma_f32_16x16x32_bf16 v[34:37], v[90:93], v[86:89], v[34:37]
	v_addc_co_u32_e32 v139, vcc, 0, v127, vcc
	v_mfma_f32_16x16x32_bf16 v[38:41], v[98:101], v[86:89], v[38:41]
	v_mfma_f32_16x16x32_bf16 v[42:45], v[106:109], v[86:89], v[42:45]
	s_nop 0
	s_nop 0
	s_waitcnt vmcnt(0)
	v_mfma_f32_16x16x32_bf16 v[62:65], v[152:155], v[172:175], v[62:65]
	v_mfma_f32_16x16x32_bf16 v[66:69], v[152:155], v[176:179], v[66:69]
	v_mfma_f32_16x16x32_bf16 v[78:81], v[152:155], v[192:195], v[78:81]
	v_mfma_f32_16x16x32_bf16 v[26:29], v[152:155], v[200:203], v[26:29]
	s_nop 0
	v_mfma_f32_16x16x32_bf16 v[94:97], v[164:167], v[176:179], v[94:97]
	s_barrier
	v_mfma_f32_16x16x32_bf16 v[30:33], v[160:163], v[172:175], v[30:33]
	v_mfma_f32_16x16x32_bf16 v[82:85], v[164:167], v[172:175], v[82:85]
	v_mfma_f32_16x16x32_bf16 v[46:49], v[168:171], v[172:175], v[46:49]
	v_mfma_f32_16x16x32_bf16 v[54:57], v[160:163], v[176:179], v[54:57]
	v_mfma_f32_16x16x32_bf16 v[58:61], v[160:163], v[192:195], v[58:61]
	v_mfma_f32_16x16x32_bf16 v[34:37], v[160:163], v[200:203], v[34:37]
	v_mfma_f32_16x16x32_bf16 v[50:53], v[168:171], v[176:179], v[50:53]
	v_mfma_f32_16x16x32_bf16 v[86:89], v[164:167], v[192:195], v[102:105]
	v_mfma_f32_16x16x32_bf16 v[70:73], v[168:171], v[192:195], v[70:73]
	v_mfma_f32_16x16x32_bf16 v[38:41], v[164:167], v[200:203], v[38:41]
	v_mfma_f32_16x16x32_bf16 v[42:45], v[168:171], v[200:203], v[42:45]
	v_mfma_f32_16x16x32_bf16 v[62:65], v[156:159], v[180:183], v[62:65]
	v_mfma_f32_16x16x32_bf16 v[90:93], v[216:219], v[188:191], v[94:97]
	s_nop 2
	v_add_u32_e32 v94, s15, v11
	v_ashrrev_i32_e32 v95, 31, v94
	v_lshlrev_b64 v[94:95], 11, v[94:95]
	v_mfma_f32_16x16x32_bf16 v[30:33], v[212:215], v[180:183], v[30:33]
	v_mfma_f32_16x16x32_bf16 v[82:85], v[216:219], v[180:183], v[82:85]
	v_mfma_f32_16x16x32_bf16 v[46:49], v[208:211], v[180:183], v[46:49]
	v_mfma_f32_16x16x32_bf16 v[54:57], v[212:215], v[188:191], v[54:57]
	v_mfma_f32_16x16x32_bf16 v[58:61], v[212:215], v[196:199], v[58:61]
	v_mfma_f32_16x16x32_bf16 v[34:37], v[212:215], v[204:207], v[34:37]
	v_lshl_add_u64 v[74:75], s[6:7], 0, v[94:95]
	v_lshl_add_u64 v[74:75], s[2:3], 1, v[74:75]
	v_lshl_add_u64 v[94:95], v[74:75], 0, v[0:1]
	v_mfma_f32_16x16x32_bf16 v[66:69], v[156:159], v[188:191], v[66:69]
	v_mfma_f32_16x16x32_bf16 v[78:81], v[156:159], v[196:199], v[78:81]
	v_mfma_f32_16x16x32_bf16 v[26:29], v[156:159], v[204:207], v[26:29]
	v_mfma_f32_16x16x32_bf16 v[50:53], v[208:211], v[188:191], v[50:53]
	v_mfma_f32_16x16x32_bf16 v[86:89], v[216:219], v[196:199], v[86:89]
	v_mfma_f32_16x16x32_bf16 v[70:73], v[208:211], v[196:199], v[70:73]
	v_mfma_f32_16x16x32_bf16 v[38:41], v[216:219], v[204:207], v[38:41]
	v_mfma_f32_16x16x32_bf16 v[42:45], v[208:211], v[204:207], v[42:45]
	ds_write_b128 v12, v[62:65]
	ds_write_b128 v13, v[30:33]
	ds_write_b128 v14, v[82:85]
	ds_write_b128 v15, v[46:49]
	ds_write_b128 v12, v[66:69] offset:4096
	ds_write_b128 v13, v[54:57] offset:4096
	ds_write_b128 v14, v[90:93] offset:4096
	ds_write_b128 v15, v[50:53] offset:4096
	ds_write_b128 v12, v[78:81] offset:8192
	ds_write_b128 v13, v[58:61] offset:8192
	ds_write_b128 v14, v[86:89] offset:8192
	ds_write_b128 v15, v[70:73] offset:8192
	ds_write_b128 v12, v[26:29] offset:12288
	ds_write_b128 v13, v[34:37] offset:12288
	ds_write_b128 v14, v[38:41] offset:12288
	ds_write_b128 v15, v[42:45] offset:12288
	s_waitcnt lgkmcnt(0)
	s_waitcnt lgkmcnt(0)
	s_barrier
	ds_read_b128 v[26:29], v16
	ds_read_b128 v[30:33], v16 offset:16384
	ds_read_b128 v[34:37], v17
	ds_read_b128 v[38:41], v17 offset:16384
	ds_read_b128 v[42:45], v16 offset:32768
	ds_read_b128 v[46:49], v16 offset:49152
	ds_read_b128 v[50:53], v17 offset:32768
	ds_read_b128 v[54:57], v17 offset:49152
	ds_read_b128 v[58:61], v18
	ds_read_b128 v[62:65], v19
	ds_read_b128 v[66:69], v20
	ds_read_b128 v[70:73], v21
	ds_read_b128 v[74:77], v22
	ds_read_b128 v[78:81], v23
	ds_read_b128 v[82:85], v24
	ds_read_b128 v[86:89], v25
	s_waitcnt lgkmcnt(14)
	v_pk_add_f32 v[28:29], v[28:29], 0 op_sel_hi:[1,0]
	v_pk_add_f32 v[26:27], v[26:27], 0 op_sel_hi:[1,0]
	s_waitcnt lgkmcnt(13)
	v_pk_add_f32 v[36:37], v[36:37], 0 op_sel_hi:[1,0]
	v_pk_add_f32 v[34:35], v[34:35], 0 op_sel_hi:[1,0]
	v_pk_add_f32 v[28:29], v[28:29], v[32:33]
	v_pk_add_f32 v[26:27], v[26:27], v[30:31]
	s_waitcnt lgkmcnt(12)
	v_pk_add_f32 v[30:31], v[36:37], v[40:41]
	v_pk_add_f32 v[32:33], v[34:35], v[38:39]
	s_waitcnt lgkmcnt(11)
	v_pk_add_f32 v[28:29], v[28:29], v[44:45]
	v_pk_add_f32 v[26:27], v[26:27], v[42:43]
	s_waitcnt lgkmcnt(9)
	v_pk_add_f32 v[30:31], v[30:31], v[52:53]
	v_pk_add_f32 v[32:33], v[32:33], v[50:51]
	v_pk_add_f32 v[28:29], v[28:29], v[48:49]
	v_pk_add_f32 v[26:27], v[26:27], v[46:47]
	s_waitcnt lgkmcnt(8)
	v_pk_add_f32 v[30:31], v[30:31], v[56:57]
	v_pk_add_f32 v[32:33], v[32:33], v[54:55]
	s_waitcnt lgkmcnt(7)
	v_pk_add_f32 v[28:29], v[28:29], v[60:61]
	v_pk_add_f32 v[26:27], v[26:27], v[58:59]
	s_waitcnt lgkmcnt(6)
	v_pk_add_f32 v[30:31], v[30:31], v[64:65]
	v_pk_add_f32 v[32:33], v[32:33], v[62:63]
	s_waitcnt lgkmcnt(5)
	v_pk_add_f32 v[28:29], v[28:29], v[68:69]
	v_pk_add_f32 v[26:27], v[26:27], v[66:67]
	s_waitcnt lgkmcnt(4)
	v_pk_add_f32 v[30:31], v[30:31], v[72:73]
	v_pk_add_f32 v[32:33], v[32:33], v[70:71]
	s_waitcnt lgkmcnt(3)
	v_pk_add_f32 v[28:29], v[28:29], v[76:77]
	v_pk_add_f32 v[26:27], v[26:27], v[74:75]
	s_waitcnt lgkmcnt(2)
	v_pk_add_f32 v[30:31], v[30:31], v[80:81]
	v_pk_add_f32 v[32:33], v[32:33], v[78:79]
	s_waitcnt lgkmcnt(1)
	v_pk_add_f32 v[28:29], v[28:29], v[84:85]
	v_pk_add_f32 v[26:27], v[26:27], v[82:83]
	s_waitcnt lgkmcnt(0)
	v_pk_add_f32 v[30:31], v[30:31], v[88:89]
	v_pk_add_f32 v[32:33], v[32:33], v[86:87]
	v_cvt_pk_bf16_f32 v26, v26, v27
	v_cvt_pk_bf16_f32 v27, v28, v29
	s_nop 0
	v_cvt_pk_bf16_f32 v28, v32, v33
	v_cvt_pk_bf16_f32 v29, v30, v31
	s_nop 0
	global_store_dwordx4 v[94:95], v[26:29], off sc0 sc1
	s_nop 1
	s_cbranch_scc1 .LBB0_1016
